# K-loop priorities inverted: loading half at priority 1, MFMA-issuing half at 0
# baseline (speedup 1.0000x reference)
.LBB0_131:
	s_add_i32 s74, s44, 2
	s_add_u32 s75, s38, 0x80
	s_addc_u32 s45, s39, 0
	s_add_i32 s94, 0, 0x10000
	s_cmp_eq_u32 s11, s44
	s_cselect_b32 s45, s93, s45
	s_cselect_b32 s44, s92, s75
	s_cselect_b32 s89, s99, s57
	s_cselect_b32 s88, s98, s56
	s_add_i32 s75, 0, 0x14000
	v_add_u32_e32 v142, s94, v242
	v_add_u32_e32 v158, s100, v242
	ds_read_b128 v[130:133], v142
	ds_read_b128 v[134:137], v142 offset:1024
	ds_read_b128 v[138:141], v142 offset:2048
	ds_read_b128 v[142:145], v142 offset:3072
	ds_read_b128 v[146:149], v158
	ds_read_b128 v[150:153], v158 offset:1024
	ds_read_b128 v[154:157], v158 offset:2048
	ds_read_b128 v[158:161], v158 offset:3072
	v_lshl_add_u64 v[212:213], s[38:39], 0, v[176:177]
	s_add_i32 m0, s3, 0xc000
	ds_read_b128 v[180:183], v243
	ds_read_b128 v[184:187], v243 offset:1024
	ds_read_b128 v[188:191], v243 offset:2048
	ds_read_b128 v[192:195], v243 offset:3072
	ds_read_b128 v[196:199], v243 offset:4096
	ds_read_b128 v[200:203], v243 offset:5120
	ds_read_b128 v[204:207], v243 offset:6144
	ds_read_b128 v[208:211], v243 offset:7168
	global_load_lds_dwordx4 v[212:213], off
	v_lshl_add_u64 v[212:213], s[38:39], 0, v[178:179]
	s_add_i32 m0, s3, 0xe000
	s_nop 0
	global_load_lds_dwordx4 v[212:213], off
	s_waitcnt vmcnt(8)
	s_waitcnt lgkmcnt(0)
	s_barrier
	s_setprio 0
	s_waitcnt lgkmcnt(0)
	v_mfma_f32_16x16x32_bf16 v[126:129], v[130:133], v[180:183], v[126:129]
	v_mfma_f32_16x16x32_bf16 v[122:125], v[138:141], v[180:183], v[122:125]
	v_mfma_f32_16x16x32_bf16 v[110:113], v[130:133], v[188:191], v[110:113]
	v_mfma_f32_16x16x32_bf16 v[106:109], v[138:141], v[188:191], v[106:109]
	v_mfma_f32_16x16x32_bf16 v[94:97], v[130:133], v[196:199], v[94:97]
	v_mfma_f32_16x16x32_bf16 v[90:93], v[138:141], v[196:199], v[90:93]
	v_mfma_f32_16x16x32_bf16 v[78:81], v[130:133], v[204:207], v[78:81]
	v_mfma_f32_16x16x32_bf16 v[74:77], v[138:141], v[204:207], v[74:77]
	v_mfma_f32_16x16x32_bf16 v[126:129], v[134:137], v[184:187], v[126:129]
	v_mfma_f32_16x16x32_bf16 v[122:125], v[142:145], v[184:187], v[122:125]
	v_mfma_f32_16x16x32_bf16 v[110:113], v[134:137], v[192:195], v[110:113]
	v_mfma_f32_16x16x32_bf16 v[106:109], v[142:145], v[192:195], v[106:109]
	v_mfma_f32_16x16x32_bf16 v[94:97], v[134:137], v[200:203], v[94:97]
	v_mfma_f32_16x16x32_bf16 v[90:93], v[142:145], v[200:203], v[90:93]
	v_mfma_f32_16x16x32_bf16 v[78:81], v[134:137], v[208:211], v[78:81]
	v_mfma_f32_16x16x32_bf16 v[74:77], v[142:145], v[208:211], v[74:77]
	s_setprio 1
	s_setprio 0
	v_mfma_f32_16x16x32_bf16 v[118:121], v[146:149], v[180:183], v[118:121]
	v_mfma_f32_16x16x32_bf16 v[114:117], v[154:157], v[180:183], v[114:117]
	v_mfma_f32_16x16x32_bf16 v[102:105], v[146:149], v[188:191], v[102:105]
	v_mfma_f32_16x16x32_bf16 v[98:101], v[154:157], v[188:191], v[98:101]
	v_mfma_f32_16x16x32_bf16 v[86:89], v[146:149], v[196:199], v[86:89]
	v_mfma_f32_16x16x32_bf16 v[82:85], v[154:157], v[196:199], v[82:85]
	v_mfma_f32_16x16x32_bf16 v[70:73], v[146:149], v[204:207], v[70:73]
	v_mfma_f32_16x16x32_bf16 v[66:69], v[154:157], v[204:207], v[66:69]
	v_mfma_f32_16x16x32_bf16 v[118:121], v[150:153], v[184:187], v[118:121]
	v_mfma_f32_16x16x32_bf16 v[114:117], v[158:161], v[184:187], v[114:117]
	v_mfma_f32_16x16x32_bf16 v[102:105], v[150:153], v[192:195], v[102:105]
	v_mfma_f32_16x16x32_bf16 v[98:101], v[158:161], v[192:195], v[98:101]
	v_mfma_f32_16x16x32_bf16 v[86:89], v[150:153], v[200:203], v[86:89]
	v_mfma_f32_16x16x32_bf16 v[82:85], v[158:161], v[200:203], v[82:85]
	v_mfma_f32_16x16x32_bf16 v[70:73], v[150:153], v[208:211], v[70:73]
	v_mfma_f32_16x16x32_bf16 v[66:69], v[158:161], v[208:211], v[66:69]
	s_setprio 1
	s_barrier
	s_add_i32 s94, s94, s77
	v_lshl_add_u64 v[212:213], s[88:89], 0, v[166:167]
	s_mov_b32 m0, s94
	ds_read_b128 v[180:183], v243 offset:16384
	ds_read_b128 v[184:187], v243 offset:17408
	ds_read_b128 v[188:191], v243 offset:18432
	ds_read_b128 v[192:195], v243 offset:19456
	ds_read_b128 v[196:199], v243 offset:20480
	ds_read_b128 v[200:203], v243 offset:21504
	ds_read_b128 v[204:207], v243 offset:22528
	ds_read_b128 v[208:211], v243 offset:23552
	global_load_lds_dwordx4 v[212:213], off
	s_add_i32 m0, s94, 0x2000
	v_lshl_add_u64 v[214:215], s[88:89], 0, v[170:171]
	s_add_u32 s88, s88, s96
	s_addc_u32 s89, s89, 0
	s_add_i32 s75, s75, s77
	global_load_lds_dwordx4 v[214:215], off
	v_lshl_add_u64 v[216:217], s[88:89], 0, v[166:167]
	s_mov_b32 m0, s75
	v_lshl_add_u64 v[218:219], s[88:89], 0, v[170:171]
	global_load_lds_dwordx4 v[216:217], off
	s_add_i32 m0, s75, 0x2000
	v_lshl_add_u64 v[220:221], s[44:45], 0, v[164:165]
	global_load_lds_dwordx4 v[218:219], off
	s_mov_b32 m0, s3
	v_lshl_add_u64 v[222:223], s[44:45], 0, v[168:169]
	global_load_lds_dwordx4 v[220:221], off
	s_mov_b32 m0, s78
	s_nop 0
	global_load_lds_dwordx4 v[222:223], off
	s_waitcnt vmcnt(8)
	s_waitcnt lgkmcnt(0)
	s_barrier
	s_setprio 0
	s_waitcnt lgkmcnt(0)
	v_mfma_f32_16x16x32_bf16 v[62:65], v[130:133], v[180:183], v[62:65]
	v_mfma_f32_16x16x32_bf16 v[58:61], v[138:141], v[180:183], v[58:61]
	v_mfma_f32_16x16x32_bf16 v[46:49], v[130:133], v[188:191], v[46:49]
	v_mfma_f32_16x16x32_bf16 v[42:45], v[138:141], v[188:191], v[42:45]
	v_mfma_f32_16x16x32_bf16 v[30:33], v[130:133], v[196:199], v[30:33]
	v_mfma_f32_16x16x32_bf16 v[26:29], v[138:141], v[196:199], v[26:29]
	v_mfma_f32_16x16x32_bf16 v[14:17], v[130:133], v[204:207], v[14:17]
	v_mfma_f32_16x16x32_bf16 v[10:13], v[138:141], v[204:207], v[10:13]
	v_mfma_f32_16x16x32_bf16 v[62:65], v[134:137], v[184:187], v[62:65]
	v_mfma_f32_16x16x32_bf16 v[58:61], v[142:145], v[184:187], v[58:61]
	v_mfma_f32_16x16x32_bf16 v[46:49], v[134:137], v[192:195], v[46:49]
	v_mfma_f32_16x16x32_bf16 v[42:45], v[142:145], v[192:195], v[42:45]
	v_mfma_f32_16x16x32_bf16 v[30:33], v[134:137], v[200:203], v[30:33]
	v_mfma_f32_16x16x32_bf16 v[26:29], v[142:145], v[200:203], v[26:29]
	v_mfma_f32_16x16x32_bf16 v[14:17], v[134:137], v[208:211], v[14:17]
	v_mfma_f32_16x16x32_bf16 v[10:13], v[142:145], v[208:211], v[10:13]
	s_setprio 1
	s_setprio 0
	v_mfma_f32_16x16x32_bf16 v[54:57], v[146:149], v[180:183], v[54:57]
	v_mfma_f32_16x16x32_bf16 v[50:53], v[154:157], v[180:183], v[50:53]
	v_mfma_f32_16x16x32_bf16 v[38:41], v[146:149], v[188:191], v[38:41]
	v_mfma_f32_16x16x32_bf16 v[34:37], v[154:157], v[188:191], v[34:37]
	v_mfma_f32_16x16x32_bf16 v[22:25], v[146:149], v[196:199], v[22:25]
	v_mfma_f32_16x16x32_bf16 v[18:21], v[154:157], v[196:199], v[18:21]
	v_mfma_f32_16x16x32_bf16 v[6:9], v[146:149], v[204:207], v[6:9]
	v_mfma_f32_16x16x32_bf16 v[2:5], v[154:157], v[204:207], v[2:5]
	v_mfma_f32_16x16x32_bf16 v[54:57], v[150:153], v[184:187], v[54:57]
	v_mfma_f32_16x16x32_bf16 v[50:53], v[158:161], v[184:187], v[50:53]
	v_mfma_f32_16x16x32_bf16 v[38:41], v[150:153], v[192:195], v[38:41]
	v_mfma_f32_16x16x32_bf16 v[34:37], v[158:161], v[192:195], v[34:37]
	v_mfma_f32_16x16x32_bf16 v[22:25], v[150:153], v[200:203], v[22:25]
	v_mfma_f32_16x16x32_bf16 v[18:21], v[158:161], v[200:203], v[18:21]
	v_mfma_f32_16x16x32_bf16 v[6:9], v[150:153], v[208:211], v[6:9]
	v_mfma_f32_16x16x32_bf16 v[2:5], v[158:161], v[208:211], v[2:5]
	s_setprio 1
	s_barrier
	s_add_i32 s75, 0, 0x18000
	s_add_i32 s88, 0, 0x1c000
	v_add_u32_e32 v142, s75, v242
	s_add_i32 vcc_lo, s100, 0x8000
	v_add_u32_e32 v158, vcc_lo, v242
	ds_read_b128 v[130:133], v142
	ds_read_b128 v[134:137], v142 offset:1024
	ds_read_b128 v[138:141], v142 offset:2048
	ds_read_b128 v[142:145], v142 offset:3072
	ds_read_b128 v[146:149], v158
	ds_read_b128 v[150:153], v158 offset:1024
	ds_read_b128 v[154:157], v158 offset:2048
	ds_read_b128 v[158:161], v158 offset:3072
	s_add_u32 s44, s44, s96
	s_addc_u32 s45, s45, 0
	s_mov_b32 m0, s9
	v_lshl_add_u64 v[224:225], s[44:45], 0, v[164:165]
	ds_read_b128 v[180:183], v243 offset:32768
	ds_read_b128 v[184:187], v243 offset:33792
	ds_read_b128 v[188:191], v243 offset:34816
	ds_read_b128 v[192:195], v243 offset:35840
	ds_read_b128 v[196:199], v243 offset:36864
	ds_read_b128 v[200:203], v243 offset:37888
	ds_read_b128 v[204:207], v243 offset:38912
	ds_read_b128 v[208:211], v243 offset:39936
	global_load_lds_dwordx4 v[224:225], off
	v_lshl_add_u64 v[224:225], s[44:45], 0, v[168:169]
	s_mov_b32 m0, s86
	s_nop 0
	global_load_lds_dwordx4 v[224:225], off
	s_waitcnt vmcnt(8)
	s_waitcnt lgkmcnt(0)
	s_barrier
	s_setprio 0
	s_waitcnt lgkmcnt(0)
	v_mfma_f32_16x16x32_bf16 v[126:129], v[130:133], v[180:183], v[126:129]
	v_mfma_f32_16x16x32_bf16 v[122:125], v[138:141], v[180:183], v[122:125]
	v_mfma_f32_16x16x32_bf16 v[110:113], v[130:133], v[188:191], v[110:113]
	v_mfma_f32_16x16x32_bf16 v[106:109], v[138:141], v[188:191], v[106:109]
	v_mfma_f32_16x16x32_bf16 v[94:97], v[130:133], v[196:199], v[94:97]
	v_mfma_f32_16x16x32_bf16 v[90:93], v[138:141], v[196:199], v[90:93]
	v_mfma_f32_16x16x32_bf16 v[78:81], v[130:133], v[204:207], v[78:81]
	v_mfma_f32_16x16x32_bf16 v[74:77], v[138:141], v[204:207], v[74:77]
	v_mfma_f32_16x16x32_bf16 v[126:129], v[134:137], v[184:187], v[126:129]
	v_mfma_f32_16x16x32_bf16 v[122:125], v[142:145], v[184:187], v[122:125]
	v_mfma_f32_16x16x32_bf16 v[110:113], v[134:137], v[192:195], v[110:113]
	v_mfma_f32_16x16x32_bf16 v[106:109], v[142:145], v[192:195], v[106:109]
	v_mfma_f32_16x16x32_bf16 v[94:97], v[134:137], v[200:203], v[94:97]
	v_mfma_f32_16x16x32_bf16 v[90:93], v[142:145], v[200:203], v[90:93]
	v_mfma_f32_16x16x32_bf16 v[78:81], v[134:137], v[208:211], v[78:81]
	v_mfma_f32_16x16x32_bf16 v[74:77], v[142:145], v[208:211], v[74:77]
	s_setprio 1
	s_setprio 0
	v_mfma_f32_16x16x32_bf16 v[118:121], v[146:149], v[180:183], v[118:121]
	v_mfma_f32_16x16x32_bf16 v[114:117], v[154:157], v[180:183], v[114:117]
	v_mfma_f32_16x16x32_bf16 v[102:105], v[146:149], v[188:191], v[102:105]
	v_mfma_f32_16x16x32_bf16 v[98:101], v[154:157], v[188:191], v[98:101]
	v_mfma_f32_16x16x32_bf16 v[86:89], v[146:149], v[196:199], v[86:89]
	v_mfma_f32_16x16x32_bf16 v[82:85], v[154:157], v[196:199], v[82:85]
	v_mfma_f32_16x16x32_bf16 v[70:73], v[146:149], v[204:207], v[70:73]
	v_mfma_f32_16x16x32_bf16 v[66:69], v[154:157], v[204:207], v[66:69]
	v_mfma_f32_16x16x32_bf16 v[118:121], v[150:153], v[184:187], v[118:121]
	v_mfma_f32_16x16x32_bf16 v[114:117], v[158:161], v[184:187], v[114:117]
	v_mfma_f32_16x16x32_bf16 v[102:105], v[150:153], v[192:195], v[102:105]
	v_mfma_f32_16x16x32_bf16 v[98:101], v[158:161], v[192:195], v[98:101]
	v_mfma_f32_16x16x32_bf16 v[86:89], v[150:153], v[200:203], v[86:89]
	v_mfma_f32_16x16x32_bf16 v[82:85], v[158:161], v[200:203], v[82:85]
	v_mfma_f32_16x16x32_bf16 v[70:73], v[150:153], v[208:211], v[70:73]
	v_mfma_f32_16x16x32_bf16 v[66:69], v[158:161], v[208:211], v[66:69]
	s_setprio 1
	s_barrier
	s_add_i32 s44, s75, s77
	v_lshl_add_u64 v[212:213], v[212:213], 0, s[4:5]
	s_mov_b32 m0, s44
	ds_read_b128 v[180:183], v243 offset:49152
	ds_read_b128 v[184:187], v243 offset:50176
	ds_read_b128 v[188:191], v243 offset:51200
	ds_read_b128 v[192:195], v243 offset:52224
	ds_read_b128 v[196:199], v243 offset:53248
	ds_read_b128 v[200:203], v243 offset:54272
	ds_read_b128 v[204:207], v243 offset:55296
	ds_read_b128 v[208:211], v243 offset:56320
	global_load_lds_dwordx4 v[212:213], off
	v_lshl_add_u64 v[212:213], v[214:215], 0, s[4:5]
	s_add_i32 m0, s44, 0x2000
	s_add_i32 s44, s88, s77
	global_load_lds_dwordx4 v[212:213], off
	v_lshl_add_u64 v[212:213], v[216:217], 0, s[4:5]
	s_mov_b32 m0, s44
	s_nop 0
	global_load_lds_dwordx4 v[212:213], off
	v_lshl_add_u64 v[212:213], v[218:219], 0, s[4:5]
	s_add_i32 m0, s44, 0x2000
	s_nop 0
	global_load_lds_dwordx4 v[212:213], off
	v_lshl_add_u64 v[212:213], v[220:221], 0, s[4:5]
	s_mov_b32 m0, s80
	s_nop 0
	global_load_lds_dwordx4 v[212:213], off
	v_lshl_add_u64 v[212:213], v[222:223], 0, s[4:5]
	s_mov_b32 m0, s84
	s_nop 0
	global_load_lds_dwordx4 v[212:213], off
	s_waitcnt vmcnt(8)
	s_waitcnt lgkmcnt(0)
	s_barrier
	s_setprio 0
	s_waitcnt lgkmcnt(0)
	v_mfma_f32_16x16x32_bf16 v[62:65], v[130:133], v[180:183], v[62:65]
	v_mfma_f32_16x16x32_bf16 v[58:61], v[138:141], v[180:183], v[58:61]
	v_mfma_f32_16x16x32_bf16 v[46:49], v[130:133], v[188:191], v[46:49]
	v_mfma_f32_16x16x32_bf16 v[42:45], v[138:141], v[188:191], v[42:45]
	v_mfma_f32_16x16x32_bf16 v[30:33], v[130:133], v[196:199], v[30:33]
	v_mfma_f32_16x16x32_bf16 v[26:29], v[138:141], v[196:199], v[26:29]
	v_mfma_f32_16x16x32_bf16 v[14:17], v[130:133], v[204:207], v[14:17]
	v_mfma_f32_16x16x32_bf16 v[10:13], v[138:141], v[204:207], v[10:13]
	v_mfma_f32_16x16x32_bf16 v[62:65], v[134:137], v[184:187], v[62:65]
	v_mfma_f32_16x16x32_bf16 v[58:61], v[142:145], v[184:187], v[58:61]
	v_mfma_f32_16x16x32_bf16 v[46:49], v[134:137], v[192:195], v[46:49]
	v_mfma_f32_16x16x32_bf16 v[42:45], v[142:145], v[192:195], v[42:45]
	v_mfma_f32_16x16x32_bf16 v[30:33], v[134:137], v[200:203], v[30:33]
	v_mfma_f32_16x16x32_bf16 v[26:29], v[142:145], v[200:203], v[26:29]
	v_mfma_f32_16x16x32_bf16 v[14:17], v[134:137], v[208:211], v[14:17]
	v_mfma_f32_16x16x32_bf16 v[10:13], v[142:145], v[208:211], v[10:13]
	s_setprio 1
	s_setprio 0
	v_mfma_f32_16x16x32_bf16 v[54:57], v[146:149], v[180:183], v[54:57]
	v_mfma_f32_16x16x32_bf16 v[50:53], v[154:157], v[180:183], v[50:53]
	v_mfma_f32_16x16x32_bf16 v[38:41], v[146:149], v[188:191], v[38:41]
	v_mfma_f32_16x16x32_bf16 v[34:37], v[154:157], v[188:191], v[34:37]
	v_mfma_f32_16x16x32_bf16 v[22:25], v[146:149], v[196:199], v[22:25]
	v_mfma_f32_16x16x32_bf16 v[18:21], v[154:157], v[196:199], v[18:21]
	v_mfma_f32_16x16x32_bf16 v[6:9], v[146:149], v[204:207], v[6:9]
	v_mfma_f32_16x16x32_bf16 v[2:5], v[154:157], v[204:207], v[2:5]
	v_mfma_f32_16x16x32_bf16 v[54:57], v[150:153], v[184:187], v[54:57]
	v_mfma_f32_16x16x32_bf16 v[50:53], v[158:161], v[184:187], v[50:53]
	v_mfma_f32_16x16x32_bf16 v[38:41], v[150:153], v[192:195], v[38:41]
	v_mfma_f32_16x16x32_bf16 v[34:37], v[158:161], v[192:195], v[34:37]
	v_mfma_f32_16x16x32_bf16 v[22:25], v[150:153], v[200:203], v[22:25]
	v_mfma_f32_16x16x32_bf16 v[18:21], v[158:161], v[200:203], v[18:21]
	v_mfma_f32_16x16x32_bf16 v[6:9], v[150:153], v[208:211], v[6:9]
	v_mfma_f32_16x16x32_bf16 v[2:5], v[158:161], v[208:211], v[2:5]
	s_setprio 1
	s_barrier
	s_add_u32 s38, s38, 0x100
	s_addc_u32 s39, s39, 0
	s_add_u32 s56, s56, 0x100
	s_addc_u32 s57, s57, 0
	s_cmp_ge_u32 s74, s83
	s_mov_b32 s44, s74
	s_cbranch_scc0 .LBB0_131
	s_and_b64 vcc, exec, s[30:31]
	s_cbranch_vccz .LBB0_134
	s_barrier
